# adds P4 residual loads as 16-byte loads with permlane layout restore, five row groups in flight
# speedup vs baseline: 1.0340x; 1.0069x over previous
.LBB0_391:
	s_lshl_b32 s39, s14, 8
	v_add_u32_e32 v176, s39, v180
	v_lshl_or_b32 v128, s46, 8, v182
	v_ashrrev_i32_e32 v177, 31, v176
	v_ashrrev_i32_e32 v129, 31, v128
	v_lshlrev_b64 v[130:131], 11, v[176:177]
	v_lshl_add_u64 v[132:133], s[16:17], 0, v[130:131]
	v_lshlrev_b64 v[130:131], 1, v[128:129]
	v_lshl_add_u64 v[132:133], v[132:133], 0, v[130:131]
	s_mov_b64 s[80:81], 0x8000
	s_mov_b64 s[82:83], 0x28000
	v_lshrrev_b32_e32 v252, 4, v203
	v_lshlrev_b32_e32 v252, 3, v252
	v_mov_b32_e32 v253, 0
	v_lshl_add_u64 v[254:255], v[132:133], 0, v[252:253]
	global_load_dwordx4 v[210:213], v[254:255], off
	global_load_dwordx4 v[214:217], v[254:255], off offset:256
	v_lshl_add_u64 v[254:255], v[254:255], 0, s[80:81]
	global_load_dwordx4 v[218:221], v[254:255], off
	global_load_dwordx4 v[222:225], v[254:255], off offset:256
	v_lshl_add_u64 v[254:255], v[254:255], 0, s[80:81]
	global_load_dwordx4 v[226:229], v[254:255], off
	global_load_dwordx4 v[230:233], v[254:255], off offset:256
	v_lshl_add_u64 v[254:255], v[254:255], 0, s[80:81]
	global_load_dwordx4 v[234:237], v[254:255], off
	global_load_dwordx4 v[238:241], v[254:255], off offset:256
	v_lshl_add_u64 v[254:255], v[254:255], 0, s[82:83]
	global_load_dwordx4 v[242:245], v[254:255], off
	global_load_dwordx4 v[246:249], v[254:255], off offset:256
	v_lshl_add_u64 v[254:255], v[254:255], 0, s[80:81]
	v_or_b32_e32 v140, 16, v176
	v_ashrrev_i32_e32 v141, 31, v140
	v_lshlrev_b64 v[140:141], 11, v[140:141]
	v_lshl_add_u64 v[140:141], s[16:17], 0, v[140:141]
	v_lshl_add_u64 v[140:141], v[140:141], 0, v[130:131]
	s_waitcnt vmcnt(8)
	v_permlane16_swap_b32_e32 v210, v212
	v_permlane16_swap_b32_e32 v211, v213
	v_permlane32_swap_b32_e32 v210, v212
	v_permlane32_swap_b32_e32 v211, v213
	v_permlane16_swap_b32_e32 v214, v216
	v_permlane16_swap_b32_e32 v215, v217
	v_permlane32_swap_b32_e32 v214, v216
	v_permlane32_swap_b32_e32 v215, v217
	v_mov_b32_e32 v134, v210
	v_mov_b32_e32 v135, v211
	v_mov_b32_e32 v136, v212
	v_mov_b32_e32 v137, v213
	v_mov_b32_e32 v138, v214
	v_mov_b32_e32 v139, v215
	v_mov_b32_e32 v132, v216
	v_mov_b32_e32 v133, v217
	global_load_dwordx4 v[210:213], v[254:255], off
	global_load_dwordx4 v[214:217], v[254:255], off offset:256
	v_lshl_add_u64 v[254:255], v[254:255], 0, s[80:81]
	v_lshlrev_b32_e32 v142, 16, v134
	v_and_b32_e32 v143, 0xffff0000, v134
	v_lshlrev_b32_e32 v134, 16, v135
	v_and_b32_e32 v135, 0xffff0000, v135
	v_lshlrev_b32_e32 v144, 16, v136
	v_and_b32_e32 v145, 0xffff0000, v136
	v_lshlrev_b32_e32 v136, 16, v137
	v_and_b32_e32 v137, 0xffff0000, v137
	v_lshlrev_b32_e32 v146, 16, v138
	v_and_b32_e32 v147, 0xffff0000, v138
	v_lshlrev_b32_e32 v138, 16, v139
	v_and_b32_e32 v139, 0xffff0000, v139
	v_lshlrev_b32_e32 v148, 16, v132
	v_and_b32_e32 v149, 0xffff0000, v132
	v_lshlrev_b32_e32 v132, 16, v133
	v_and_b32_e32 v133, 0xffff0000, v133
	v_pk_fma_f32 v[46:47], v[134:135], s[36:37], v[46:47] op_sel_hi:[1,0,1]
	v_pk_fma_f32 v[44:45], v[142:143], s[36:37], v[44:45] op_sel_hi:[1,0,1]
	v_pk_fma_f32 v[42:43], v[136:137], s[36:37], v[42:43] op_sel_hi:[1,0,1]
	v_pk_fma_f32 v[40:41], v[144:145], s[36:37], v[40:41] op_sel_hi:[1,0,1]
	v_pk_fma_f32 v[38:39], v[138:139], s[36:37], v[38:39] op_sel_hi:[1,0,1]
	v_pk_fma_f32 v[36:37], v[146:147], s[36:37], v[36:37] op_sel_hi:[1,0,1]
	v_pk_fma_f32 v[34:35], v[132:133], s[36:37], v[34:35] op_sel_hi:[1,0,1]
	v_pk_fma_f32 v[32:33], v[148:149], s[36:37], v[32:33] op_sel_hi:[1,0,1]
	s_nop 0
	s_waitcnt vmcnt(8)
	v_permlane16_swap_b32_e32 v218, v220
	v_permlane16_swap_b32_e32 v219, v221
	v_permlane32_swap_b32_e32 v218, v220
	v_permlane32_swap_b32_e32 v219, v221
	v_permlane16_swap_b32_e32 v222, v224
	v_permlane16_swap_b32_e32 v223, v225
	v_permlane32_swap_b32_e32 v222, v224
	v_permlane32_swap_b32_e32 v223, v225
	v_mov_b32_e32 v132, v218
	v_mov_b32_e32 v133, v219
	v_mov_b32_e32 v134, v220
	v_mov_b32_e32 v135, v221
	v_mov_b32_e32 v136, v222
	v_mov_b32_e32 v137, v223
	v_mov_b32_e32 v138, v224
	v_mov_b32_e32 v139, v225
	global_load_dwordx4 v[218:221], v[254:255], off
	global_load_dwordx4 v[222:225], v[254:255], off offset:256
	v_lshl_add_u64 v[254:255], v[254:255], 0, s[80:81]
	v_or_b32_e32 v140, 32, v176
	v_ashrrev_i32_e32 v141, 31, v140
	v_lshlrev_b64 v[140:141], 11, v[140:141]
	v_lshl_add_u64 v[140:141], s[16:17], 0, v[140:141]
	v_lshl_add_u64 v[140:141], v[140:141], 0, v[130:131]
	v_lshlrev_b32_e32 v142, 16, v132
	v_and_b32_e32 v143, 0xffff0000, v132
	v_lshlrev_b32_e32 v132, 16, v133
	v_and_b32_e32 v133, 0xffff0000, v133
	v_lshlrev_b32_e32 v144, 16, v134
	v_and_b32_e32 v145, 0xffff0000, v134
	v_lshlrev_b32_e32 v134, 16, v135
	v_and_b32_e32 v135, 0xffff0000, v135
	v_lshlrev_b32_e32 v146, 16, v136
	v_and_b32_e32 v147, 0xffff0000, v136
	v_lshlrev_b32_e32 v136, 16, v137
	v_and_b32_e32 v137, 0xffff0000, v137
	v_lshlrev_b32_e32 v148, 16, v138
	v_and_b32_e32 v149, 0xffff0000, v138
	v_lshlrev_b32_e32 v138, 16, v139
	v_and_b32_e32 v139, 0xffff0000, v139
	v_pk_fma_f32 v[90:91], v[132:133], s[36:37], v[90:91] op_sel_hi:[1,0,1]
	v_pk_fma_f32 v[88:89], v[142:143], s[36:37], v[88:89] op_sel_hi:[1,0,1]
	v_pk_fma_f32 v[58:59], v[134:135], s[36:37], v[58:59] op_sel_hi:[1,0,1]
	v_pk_fma_f32 v[56:57], v[144:145], s[36:37], v[56:57] op_sel_hi:[1,0,1]
	v_pk_fma_f32 v[54:55], v[136:137], s[36:37], v[54:55] op_sel_hi:[1,0,1]
	v_pk_fma_f32 v[52:53], v[146:147], s[36:37], v[52:53] op_sel_hi:[1,0,1]
	v_pk_fma_f32 v[50:51], v[138:139], s[36:37], v[50:51] op_sel_hi:[1,0,1]
	v_pk_fma_f32 v[48:49], v[148:149], s[36:37], v[48:49] op_sel_hi:[1,0,1]
	s_nop 0
	s_waitcnt vmcnt(8)
	v_permlane16_swap_b32_e32 v226, v228
	v_permlane16_swap_b32_e32 v227, v229
	v_permlane32_swap_b32_e32 v226, v228
	v_permlane32_swap_b32_e32 v227, v229
	v_permlane16_swap_b32_e32 v230, v232
	v_permlane16_swap_b32_e32 v231, v233
	v_permlane32_swap_b32_e32 v230, v232
	v_permlane32_swap_b32_e32 v231, v233
	v_mov_b32_e32 v132, v226
	v_mov_b32_e32 v133, v227
	v_mov_b32_e32 v134, v228
	v_mov_b32_e32 v135, v229
	v_mov_b32_e32 v136, v230
	v_mov_b32_e32 v137, v231
	v_mov_b32_e32 v138, v232
	v_mov_b32_e32 v139, v233
	global_load_dwordx4 v[226:229], v[254:255], off
	global_load_dwordx4 v[230:233], v[254:255], off offset:256
	v_or_b32_e32 v140, 48, v176
	v_ashrrev_i32_e32 v141, 31, v140
	v_lshlrev_b64 v[140:141], 11, v[140:141]
	v_lshl_add_u64 v[140:141], s[16:17], 0, v[140:141]
	v_lshl_add_u64 v[140:141], v[140:141], 0, v[130:131]
	v_lshlrev_b32_e32 v142, 16, v132
	v_and_b32_e32 v143, 0xffff0000, v132
	v_lshlrev_b32_e32 v132, 16, v133
	v_and_b32_e32 v133, 0xffff0000, v133
	v_lshlrev_b32_e32 v144, 16, v134
	v_and_b32_e32 v145, 0xffff0000, v134
	v_lshlrev_b32_e32 v134, 16, v135
	v_and_b32_e32 v135, 0xffff0000, v135
	v_lshlrev_b32_e32 v146, 16, v136
	v_and_b32_e32 v147, 0xffff0000, v136
	v_lshlrev_b32_e32 v136, 16, v137
	v_and_b32_e32 v137, 0xffff0000, v137
	v_lshlrev_b32_e32 v148, 16, v138
	v_and_b32_e32 v149, 0xffff0000, v138
	v_lshlrev_b32_e32 v138, 16, v139
	v_and_b32_e32 v139, 0xffff0000, v139
	v_pk_fma_f32 v[98:99], v[132:133], s[36:37], v[98:99] op_sel_hi:[1,0,1]
	v_pk_fma_f32 v[96:97], v[142:143], s[36:37], v[96:97] op_sel_hi:[1,0,1]
	v_pk_fma_f32 v[82:83], v[134:135], s[36:37], v[82:83] op_sel_hi:[1,0,1]
	v_pk_fma_f32 v[80:81], v[144:145], s[36:37], v[80:81] op_sel_hi:[1,0,1]
	v_pk_fma_f32 v[78:79], v[136:137], s[36:37], v[78:79] op_sel_hi:[1,0,1]
	v_pk_fma_f32 v[76:77], v[146:147], s[36:37], v[76:77] op_sel_hi:[1,0,1]
	v_pk_fma_f32 v[70:71], v[138:139], s[36:37], v[70:71] op_sel_hi:[1,0,1]
	v_pk_fma_f32 v[68:69], v[148:149], s[36:37], v[68:69] op_sel_hi:[1,0,1]
	s_nop 0
	s_waitcnt vmcnt(8)
	v_permlane16_swap_b32_e32 v234, v236
	v_permlane16_swap_b32_e32 v235, v237
	v_permlane32_swap_b32_e32 v234, v236
	v_permlane32_swap_b32_e32 v235, v237
	v_permlane16_swap_b32_e32 v238, v240
	v_permlane16_swap_b32_e32 v239, v241
	v_permlane32_swap_b32_e32 v238, v240
	v_permlane32_swap_b32_e32 v239, v241
	v_mov_b32_e32 v132, v234
	v_mov_b32_e32 v133, v235
	v_mov_b32_e32 v134, v236
	v_mov_b32_e32 v135, v237
	v_mov_b32_e32 v136, v238
	v_mov_b32_e32 v137, v239
	v_mov_b32_e32 v138, v240
	v_mov_b32_e32 v139, v241
	v_add_u32_e32 v140, 0x80, v176
	v_ashrrev_i32_e32 v141, 31, v140
	v_lshlrev_b64 v[140:141], 11, v[140:141]
	v_lshl_add_u64 v[140:141], s[16:17], 0, v[140:141]
	v_lshl_add_u64 v[140:141], v[140:141], 0, v[130:131]
	v_lshlrev_b32_e32 v142, 16, v132
	v_and_b32_e32 v143, 0xffff0000, v132
	v_lshlrev_b32_e32 v132, 16, v133
	v_and_b32_e32 v133, 0xffff0000, v133
	v_lshlrev_b32_e32 v144, 16, v134
	v_and_b32_e32 v145, 0xffff0000, v134
	v_lshlrev_b32_e32 v134, 16, v135
	v_and_b32_e32 v135, 0xffff0000, v135
	v_lshlrev_b32_e32 v146, 16, v136
	v_and_b32_e32 v147, 0xffff0000, v136
	v_lshlrev_b32_e32 v136, 16, v137
	v_and_b32_e32 v137, 0xffff0000, v137
	v_lshlrev_b32_e32 v148, 16, v138
	v_and_b32_e32 v149, 0xffff0000, v138
	v_lshlrev_b32_e32 v138, 16, v139
	v_and_b32_e32 v139, 0xffff0000, v139
	v_pk_fma_f32 v[122:123], v[132:133], s[36:37], v[122:123] op_sel_hi:[1,0,1]
	v_pk_fma_f32 v[120:121], v[142:143], s[36:37], v[120:121] op_sel_hi:[1,0,1]
	v_pk_fma_f32 v[114:115], v[134:135], s[36:37], v[114:115] op_sel_hi:[1,0,1]
	v_pk_fma_f32 v[112:113], v[144:145], s[36:37], v[112:113] op_sel_hi:[1,0,1]
	v_pk_fma_f32 v[106:107], v[136:137], s[36:37], v[106:107] op_sel_hi:[1,0,1]
	v_pk_fma_f32 v[104:105], v[146:147], s[36:37], v[104:105] op_sel_hi:[1,0,1]
	v_pk_fma_f32 v[86:87], v[138:139], s[36:37], v[86:87] op_sel_hi:[1,0,1]
	v_pk_fma_f32 v[84:85], v[148:149], s[36:37], v[84:85] op_sel_hi:[1,0,1]
	s_nop 0
	s_waitcnt vmcnt(6)
	v_permlane16_swap_b32_e32 v242, v244
	v_permlane16_swap_b32_e32 v243, v245
	v_permlane32_swap_b32_e32 v242, v244
	v_permlane32_swap_b32_e32 v243, v245
	v_permlane16_swap_b32_e32 v246, v248
	v_permlane16_swap_b32_e32 v247, v249
	v_permlane32_swap_b32_e32 v246, v248
	v_permlane32_swap_b32_e32 v247, v249
	v_mov_b32_e32 v132, v242
	v_mov_b32_e32 v133, v243
	v_mov_b32_e32 v134, v244
	v_mov_b32_e32 v135, v245
	v_mov_b32_e32 v136, v246
	v_mov_b32_e32 v137, v247
	v_mov_b32_e32 v138, v248
	v_mov_b32_e32 v139, v249
	v_add_u32_e32 v140, 0x90, v176
	v_ashrrev_i32_e32 v141, 31, v140
	v_lshlrev_b64 v[140:141], 11, v[140:141]
	v_lshl_add_u64 v[140:141], s[16:17], 0, v[140:141]
	v_lshl_add_u64 v[140:141], v[140:141], 0, v[130:131]
	v_lshlrev_b32_e32 v142, 16, v132
	v_and_b32_e32 v143, 0xffff0000, v132
	v_lshlrev_b32_e32 v132, 16, v133
	v_and_b32_e32 v133, 0xffff0000, v133
	v_lshlrev_b32_e32 v144, 16, v134
	v_and_b32_e32 v145, 0xffff0000, v134
	v_lshlrev_b32_e32 v134, 16, v135
	v_and_b32_e32 v135, 0xffff0000, v135
	v_lshlrev_b32_e32 v146, 16, v136
	v_and_b32_e32 v147, 0xffff0000, v136
	v_lshlrev_b32_e32 v136, 16, v137
	v_and_b32_e32 v137, 0xffff0000, v137
	v_lshlrev_b32_e32 v148, 16, v138
	v_and_b32_e32 v149, 0xffff0000, v138
	v_lshlrev_b32_e32 v138, 16, v139
	v_and_b32_e32 v139, 0xffff0000, v139
	v_pk_fma_f32 v[14:15], v[132:133], s[36:37], v[14:15] op_sel_hi:[1,0,1]
	v_pk_fma_f32 v[12:13], v[142:143], s[36:37], v[12:13] op_sel_hi:[1,0,1]
	v_pk_fma_f32 v[10:11], v[134:135], s[36:37], v[10:11] op_sel_hi:[1,0,1]
	v_pk_fma_f32 v[8:9], v[144:145], s[36:37], v[8:9] op_sel_hi:[1,0,1]
	v_pk_fma_f32 v[6:7], v[136:137], s[36:37], v[6:7] op_sel_hi:[1,0,1]
	v_pk_fma_f32 v[4:5], v[146:147], s[36:37], v[4:5] op_sel_hi:[1,0,1]
	v_pk_fma_f32 v[2:3], v[138:139], s[36:37], v[2:3] op_sel_hi:[1,0,1]
	v_pk_fma_f32 v[0:1], v[148:149], s[36:37], v[0:1] op_sel_hi:[1,0,1]
	s_nop 0
	s_waitcnt vmcnt(4)
	v_permlane16_swap_b32_e32 v210, v212
	v_permlane16_swap_b32_e32 v211, v213
	v_permlane32_swap_b32_e32 v210, v212
	v_permlane32_swap_b32_e32 v211, v213
	v_permlane16_swap_b32_e32 v214, v216
	v_permlane16_swap_b32_e32 v215, v217
	v_permlane32_swap_b32_e32 v214, v216
	v_permlane32_swap_b32_e32 v215, v217
	v_mov_b32_e32 v132, v210
	v_mov_b32_e32 v133, v211
	v_mov_b32_e32 v134, v212
	v_mov_b32_e32 v135, v213
	v_mov_b32_e32 v136, v214
	v_mov_b32_e32 v137, v215
	v_mov_b32_e32 v138, v216
	v_mov_b32_e32 v139, v217
	v_add_u32_e32 v140, 0xa0, v176
	v_ashrrev_i32_e32 v141, 31, v140
	v_lshlrev_b64 v[140:141], 11, v[140:141]
	v_lshl_add_u64 v[140:141], s[16:17], 0, v[140:141]
	v_lshl_add_u64 v[140:141], v[140:141], 0, v[130:131]
	v_lshlrev_b32_e32 v142, 16, v132
	v_and_b32_e32 v143, 0xffff0000, v132
	v_lshlrev_b32_e32 v132, 16, v133
	v_and_b32_e32 v133, 0xffff0000, v133
	v_lshlrev_b32_e32 v144, 16, v134
	v_and_b32_e32 v145, 0xffff0000, v134
	v_lshlrev_b32_e32 v134, 16, v135
	v_and_b32_e32 v135, 0xffff0000, v135
	v_lshlrev_b32_e32 v146, 16, v136
	v_and_b32_e32 v147, 0xffff0000, v136
	v_lshlrev_b32_e32 v136, 16, v137
	v_and_b32_e32 v137, 0xffff0000, v137
	v_lshlrev_b32_e32 v148, 16, v138
	v_and_b32_e32 v149, 0xffff0000, v138
	v_lshlrev_b32_e32 v138, 16, v139
	v_and_b32_e32 v139, 0xffff0000, v139
	v_pk_fma_f32 v[30:31], v[132:133], s[36:37], v[30:31] op_sel_hi:[1,0,1]
	v_pk_fma_f32 v[28:29], v[142:143], s[36:37], v[28:29] op_sel_hi:[1,0,1]
	v_pk_fma_f32 v[26:27], v[134:135], s[36:37], v[26:27] op_sel_hi:[1,0,1]
	v_pk_fma_f32 v[24:25], v[144:145], s[36:37], v[24:25] op_sel_hi:[1,0,1]
	v_pk_fma_f32 v[22:23], v[136:137], s[36:37], v[22:23] op_sel_hi:[1,0,1]
	v_pk_fma_f32 v[20:21], v[146:147], s[36:37], v[20:21] op_sel_hi:[1,0,1]
	v_pk_fma_f32 v[18:19], v[138:139], s[36:37], v[18:19] op_sel_hi:[1,0,1]
	v_pk_fma_f32 v[16:17], v[148:149], s[36:37], v[16:17] op_sel_hi:[1,0,1]
	v_add_u32_e32 v142, 0xb0, v176
	s_waitcnt vmcnt(2)
	v_permlane16_swap_b32_e32 v218, v220
	v_permlane16_swap_b32_e32 v219, v221
	v_permlane32_swap_b32_e32 v218, v220
	v_permlane32_swap_b32_e32 v219, v221
	v_permlane16_swap_b32_e32 v222, v224
	v_permlane16_swap_b32_e32 v223, v225
	v_permlane32_swap_b32_e32 v222, v224
	v_permlane32_swap_b32_e32 v223, v225
	v_mov_b32_e32 v134, v218
	v_mov_b32_e32 v135, v219
	v_mov_b32_e32 v136, v220
	v_mov_b32_e32 v137, v221
	v_mov_b32_e32 v138, v222
	v_mov_b32_e32 v139, v223
	v_mov_b32_e32 v140, v224
	v_mov_b32_e32 v141, v225
	v_ashrrev_i32_e32 v143, 31, v142
	v_lshlrev_b64 v[142:143], 11, v[142:143]
	v_lshl_add_u64 v[142:143], s[16:17], 0, v[142:143]
	v_lshl_add_u64 v[130:131], v[142:143], 0, v[130:131]
	v_mov_b32_e32 v142, v45
	v_mov_b32_e32 v143, v46
	v_mov_b32_e32 v144, v44
	v_mov_b32_e32 v145, v47
	v_pk_add_f32 v[142:143], v[142:143], v[144:145]
	v_mov_b32_e32 v146, v41
	v_mov_b32_e32 v147, v42
	v_and_b32_e32 v133, 64, v203
	v_xor_b32_e32 v132, 16, v203
	v_add_u32_e32 v133, 64, v133
	v_cmp_lt_i32_e32 vcc, v132, v133
	v_lshlrev_b32_e32 v148, 16, v134
	v_and_b32_e32 v149, 0xffff0000, v134
	v_lshlrev_b32_e32 v134, 16, v135
	v_and_b32_e32 v135, 0xffff0000, v135
	v_lshlrev_b32_e32 v150, 16, v136
	v_and_b32_e32 v151, 0xffff0000, v136
	v_lshlrev_b32_e32 v136, 16, v137
	v_and_b32_e32 v137, 0xffff0000, v137
	v_lshlrev_b32_e32 v152, 16, v138
	v_and_b32_e32 v153, 0xffff0000, v138
	v_lshlrev_b32_e32 v138, 16, v139
	v_and_b32_e32 v139, 0xffff0000, v139
	v_lshlrev_b32_e32 v154, 16, v140
	v_and_b32_e32 v155, 0xffff0000, v140
	v_lshlrev_b32_e32 v140, 16, v141
	v_and_b32_e32 v141, 0xffff0000, v141
	v_pk_fma_f32 v[94:95], v[134:135], s[36:37], v[94:95] op_sel_hi:[1,0,1]
	v_pk_fma_f32 v[92:93], v[148:149], s[36:37], v[92:93] op_sel_hi:[1,0,1]
	v_pk_fma_f32 v[74:75], v[136:137], s[36:37], v[74:75] op_sel_hi:[1,0,1]
	v_pk_fma_f32 v[72:73], v[150:151], s[36:37], v[72:73] op_sel_hi:[1,0,1]
	v_pk_fma_f32 v[66:67], v[138:139], s[36:37], v[66:67] op_sel_hi:[1,0,1]
	v_pk_fma_f32 v[64:65], v[152:153], s[36:37], v[64:65] op_sel_hi:[1,0,1]
	v_pk_fma_f32 v[62:63], v[140:141], s[36:37], v[62:63] op_sel_hi:[1,0,1]
	v_pk_fma_f32 v[60:61], v[154:155], s[36:37], v[60:61] op_sel_hi:[1,0,1]
	v_mov_b32_e32 v134, v40
	v_mov_b32_e32 v135, v43
	v_add_f32_e32 v141, v36, v37
	v_add_f32_e32 v149, v38, v39
	v_mov_b32_e32 v140, v32
	v_mov_b32_e32 v148, v33
	v_pk_add_f32 v[130:131], v[146:147], v[134:135]
	v_pk_add_f32 v[134:135], v[140:141], v[148:149]
	v_add_f32_e32 v140, v142, v143
	v_pk_add_f32 v[130:131], v[130:131], v[130:131] op_sel_hi:[0,1]
	v_mov_b32_e32 v152, v35
	v_add_f32_e32 v153, 0, v140
	v_mov_b32_e32 v130, v34
	v_pk_add_f32 v[130:131], v[130:131], v[152:153]
	v_cndmask_b32_e32 v132, v203, v132, vcc
	v_pk_add_f32 v[130:131], v[134:135], v[130:131]
	v_lshlrev_b32_e32 v132, 2, v132
	v_add_f32_e32 v131, v130, v131
	ds_bpermute_b32 v134, v132, v131
	v_xor_b32_e32 v130, 32, v203
	v_cmp_lt_i32_e32 vcc, v130, v133
	s_waitcnt lgkmcnt(0)
	v_add_f32_e32 v131, v131, v134
	v_cndmask_b32_e32 v130, v203, v130, vcc
	v_lshlrev_b32_e32 v130, 2, v130
	ds_bpermute_b32 v133, v130, v131
	s_waitcnt lgkmcnt(0)
	v_add_f32_e32 v131, v131, v133
	v_fmamk_f32 v134, v131, 0xbc800000, v47
	v_fmamk_f32 v140, v131, 0xbc800000, v45
	v_fmamk_f32 v142, v131, 0xbc800000, v43
	v_fmamk_f32 v146, v131, 0xbc800000, v41
	v_fmamk_f32 v133, v131, 0xbc800000, v46
	v_fmamk_f32 v135, v131, 0xbc800000, v44
	v_fmamk_f32 v141, v131, 0xbc800000, v42
	v_fmamk_f32 v143, v131, 0xbc800000, v40
	v_fmamk_f32 v148, v131, 0xbc800000, v39
	v_fmamk_f32 v152, v131, 0xbc800000, v37
	v_mul_f32_e32 v140, v140, v140
	v_mul_f32_e32 v134, v134, v134
	v_mul_f32_e32 v146, v146, v146
	v_mul_f32_e32 v142, v142, v142
	v_fmamk_f32 v147, v131, 0xbc800000, v38
	v_fmamk_f32 v149, v131, 0xbc800000, v36
	v_fmamk_f32 v154, v131, 0xbc800000, v35
	v_fmamk_f32 v156, v131, 0xbc800000, v33
	v_mul_f32_e32 v152, v152, v152
	v_mul_f32_e32 v148, v148, v148
	v_fmac_f32_e32 v140, v135, v135
	v_fmac_f32_e32 v134, v133, v133
	v_fmac_f32_e32 v146, v143, v143
	v_fmac_f32_e32 v142, v141, v141
	v_fmamk_f32 v153, v131, 0xbc800000, v34
	v_fmamk_f32 v155, v131, 0xbc800000, v32
	v_mul_f32_e32 v156, v156, v156
	v_mul_f32_e32 v154, v154, v154
	v_fmac_f32_e32 v152, v149, v149
	v_fmac_f32_e32 v148, v147, v147
	v_add_f32_e32 v133, v140, v134
	v_add_f32_e32 v134, v146, v142
	v_fmac_f32_e32 v156, v155, v155
	v_fmac_f32_e32 v154, v153, v153
	v_add_f32_e32 v135, v152, v148
	v_add_f32_e32 v133, v133, v134
	v_add_f32_e32 v140, v156, v154
	v_add_f32_e32 v133, v135, v133
	v_add_f32_e32 v133, v140, v133
	ds_bpermute_b32 v134, v132, v133
	s_waitcnt lgkmcnt(0)
	v_add_f32_e32 v133, v133, v134
	ds_bpermute_b32 v134, v130, v133
	s_waitcnt vmcnt(0)
	v_permlane16_swap_b32_e32 v226, v228
	v_permlane16_swap_b32_e32 v227, v229
	v_permlane32_swap_b32_e32 v226, v228
	v_permlane32_swap_b32_e32 v227, v229
	v_permlane16_swap_b32_e32 v230, v232
	v_permlane16_swap_b32_e32 v231, v233
	v_permlane32_swap_b32_e32 v230, v232
	v_permlane32_swap_b32_e32 v231, v233
	v_mov_b32_e32 v136, v226
	v_mov_b32_e32 v137, v227
	v_mov_b32_e32 v138, v228
	v_mov_b32_e32 v139, v229
	v_mov_b32_e32 v150, v230
	v_mov_b32_e32 v151, v231
	v_mov_b32_e32 v144, v232
	v_mov_b32_e32 v145, v233
	v_lshlrev_b32_e32 v140, 16, v136
	v_and_b32_e32 v141, 0xffff0000, v136
	v_lshlrev_b32_e32 v136, 16, v137
	v_and_b32_e32 v137, 0xffff0000, v137
	v_lshlrev_b32_e32 v142, 16, v138
	v_and_b32_e32 v143, 0xffff0000, v138
	v_lshlrev_b32_e32 v138, 16, v139
	v_and_b32_e32 v139, 0xffff0000, v139
	v_lshlrev_b32_e32 v146, 16, v150
	v_and_b32_e32 v147, 0xffff0000, v150
	v_lshlrev_b32_e32 v148, 16, v151
	v_and_b32_e32 v149, 0xffff0000, v151
	v_lshlrev_b32_e32 v150, 16, v144
	v_and_b32_e32 v151, 0xffff0000, v144
	v_lshlrev_b32_e32 v144, 16, v145
	v_and_b32_e32 v145, 0xffff0000, v145
	v_pk_fma_f32 v[126:127], v[136:137], s[36:37], v[126:127] op_sel_hi:[1,0,1]
	v_pk_fma_f32 v[124:125], v[140:141], s[36:37], v[124:125] op_sel_hi:[1,0,1]
	v_pk_fma_f32 v[118:119], v[138:139], s[36:37], v[118:119] op_sel_hi:[1,0,1]
	v_pk_fma_f32 v[116:117], v[142:143], s[36:37], v[116:117] op_sel_hi:[1,0,1]
	v_pk_fma_f32 v[110:111], v[148:149], s[36:37], v[110:111] op_sel_hi:[1,0,1]
	v_pk_fma_f32 v[108:109], v[146:147], s[36:37], v[108:109] op_sel_hi:[1,0,1]
	v_pk_fma_f32 v[102:103], v[144:145], s[36:37], v[102:103] op_sel_hi:[1,0,1]
	v_pk_fma_f32 v[100:101], v[150:151], s[36:37], v[100:101] op_sel_hi:[1,0,1]
	s_nop 0
	s_and_saveexec_b64 s[48:49], s[12:13]
	s_cbranch_execz .LBB0_393
	v_mul_f32_e32 v136, 0x3c800000, v131
	s_waitcnt lgkmcnt(0)
	v_add_f32_e32 v137, v133, v134
	ds_write_b64 v208, v[136:137]

	.amdhsa_kernel _Z10fwd_kernel4Args
		.amdhsa_group_segment_fixed_size 0
		.amdhsa_private_segment_fixed_size 0
		.amdhsa_kernarg_size 376
		.amdhsa_user_sgpr_count 2
		.amdhsa_user_sgpr_dispatch_ptr 0
		.amdhsa_user_sgpr_queue_ptr 0
		.amdhsa_user_sgpr_kernarg_segment_ptr 1
		.amdhsa_user_sgpr_dispatch_id 0
		.amdhsa_user_sgpr_kernarg_preload_length 0
		.amdhsa_user_sgpr_kernarg_preload_offset 0
		.amdhsa_user_sgpr_private_segment_size 0
		.amdhsa_uses_dynamic_stack 0
		.amdhsa_enable_private_segment 0
		.amdhsa_system_sgpr_workgroup_id_x 1
		.amdhsa_system_sgpr_workgroup_id_y 0
		.amdhsa_system_sgpr_workgroup_id_z 0
		.amdhsa_system_sgpr_workgroup_info 0
		.amdhsa_system_vgpr_workitem_id 0
		.amdhsa_next_free_vgpr 256
		.amdhsa_next_free_sgpr 98
		.amdhsa_accum_offset 256
		.amdhsa_reserve_vcc 1
		.amdhsa_float_round_mode_32 0
		.amdhsa_float_round_mode_16_64 0
		.amdhsa_float_denorm_mode_32 3
		.amdhsa_float_denorm_mode_16_64 3
		.amdhsa_dx10_clamp 1
		.amdhsa_ieee_mode 1
		.amdhsa_fp16_overflow 0
		.amdhsa_tg_split 0
		.amdhsa_exception_fp_ieee_invalid_op 0
		.amdhsa_exception_fp_denorm_src 0
		.amdhsa_exception_fp_ieee_div_zero 0
		.amdhsa_exception_fp_ieee_overflow 0
		.amdhsa_exception_fp_ieee_underflow 0
		.amdhsa_exception_fp_ieee_inexact 0
		.amdhsa_exception_int_div_zero 0
	.end_amdhsa_kernel

amdhsa.kernels:
  - .agpr_count:     0
    .args:
      - .offset:         0
        .size:           120
        .value_kind:     by_value
      - .offset:         120
        .size:           4
        .value_kind:     hidden_block_count_x
      - .offset:         124
        .size:           4
        .value_kind:     hidden_block_count_y
      - .offset:         128
        .size:           4
        .value_kind:     hidden_block_count_z
      - .offset:         132
        .size:           2
        .value_kind:     hidden_group_size_x
      - .offset:         134
        .size:           2
        .value_kind:     hidden_group_size_y
      - .offset:         136
        .size:           2
        .value_kind:     hidden_group_size_z
      - .offset:         138
        .size:           2
        .value_kind:     hidden_remainder_x
      - .offset:         140
        .size:           2
        .value_kind:     hidden_remainder_y
      - .offset:         142
        .size:           2
        .value_kind:     hidden_remainder_z
      - .offset:         160
        .size:           8
        .value_kind:     hidden_global_offset_x
      - .offset:         168
        .size:           8
        .value_kind:     hidden_global_offset_y
      - .offset:         176
        .size:           8
        .value_kind:     hidden_global_offset_z
      - .offset:         184
        .size:           2
        .value_kind:     hidden_grid_dims
      - .offset:         240
        .size:           4
        .value_kind:     hidden_dynamic_lds_size
    .group_segment_fixed_size: 0
    .kernarg_segment_align: 8
    .kernarg_segment_size: 376
    .language:       OpenCL C
    .language_version:
      - 2
      - 0
    .max_flat_workgroup_size: 512
    .name:           _Z10fwd_kernel4Args
    .private_segment_fixed_size: 0
    .sgpr_count:     104
    .sgpr_spill_count: 0
    .symbol:         _Z10fwd_kernel4Args.kd
    .uniform_work_group_size: 1
    .uses_dynamic_stack: false
    .vgpr_count:     256
    .vgpr_spill_count: 0
    .wavefront_size: 64
